# diff attn far tile: next tile's K rms-norm + LDS staging interleaved into MFMA gaps
# baseline (speedup 1.0000x reference)
; #define LAS __attribute__((address_space(3)))
; template <int MODE>
; __device__ __forceinline__ void attn_item(const AttnP& p, int b, int h, int qb, LAS unsigned char* lds) {
;     ...
;                     if (MODE == 0) {
;                         const LAS float* tab = (const LAS float*)(lds + TAB_OFF);
;                         if (qw - (kp0 + 31) >= 128) {
;                             const float cb = tab[255] - mfix;
; #pragma unroll
;                             for (int c = 0; c < NC; ++c) { ATT_QK(c, cb); ATT_TAIL(c); }
;                         } else {
;                             float binit[16];
; #pragma unroll
;                             for (int i = 0; i < 16; ++i) {
;                                 const int dist = qrow - (kp0 + crow(i, hh));
;                                 binit[i] = (dist < 0) ? -3e38f : (tab[dist > 255 ? 255 : dist] - mfix);
;                             }
; #pragma unroll
;                             for (int c = 0; c < NC; ++c) { ATT_QK(c, binit[i]); ATT_TAIL(c); }
;                         }
;                     } else {
;                         float binit[16];
;                         const LAS float* bl = (const LAS float*)(vtb + VT_BYTES) + 32 * kb2 + 4 * hh;
; #pragma unroll
;                         for (int g = 0; g < 4; ++g) {
;                             const f32x4 t = *(const LAS f32x4*)(bl + 8 * g);
; #pragma unroll
;                             for (int e = 0; e < 4; ++e) binit[4 * g + e] = (need_mask && (kp0 + crow(4 * g + e, hh) > qrow)) ? -3e38f : (t[e] - mfix);
;                         }
;                         ATT_QK(0, binit[i]); ATT_TAIL(0);
;                     }
;     ...
;                 }
; #pragma unroll
;                 for (int t2 = 0; t2 < 2; ++t2)
; #pragma unroll
;                     for (int d = 0; d < DV / 32; ++d) {
;                         const LAS unsigned char* vp = vtb + ((32 * kb2 + 16 * t2 + 4 * hh + ((lane & 15) >> 2)) * VPT + d * 32 + 16 * ((lane >> 4) & 1) + 4 * (lane & 3)) * 2;
;                         const s16x4 lo = vtr(vp), hi = vtr(vp + 8 * VPT * 2);
;                         const bf16x8 va = __builtin_shufflevector(lo, hi, 0, 1, 2, 3, 4, 5, 6, 7);
; #pragma unroll
;                         for (int c = 0; c < NC; ++c) O[c][d] = MFMA32(va, pb[c][t2], O[c][d]);
;                     }
.Lfar_tile:
	s_andn2_b64 vcc, exec, s[6:7]
	s_cbranch_vccnz .Lfar_tile_last
	s_xor_b32 s2, s5, 1
	s_mul_i32 s2, s2, 0x9500
	v_add_u32_e32 v243, v242, v235
	ds_read_b128 v[244:247], v243 offset:8704
	ds_read_b128 v[248:251], v243 offset:8736
	ds_read_b128 v[194:197], v243 offset:8768
	ds_read_b128 v[198:201], v243 offset:8800
	ds_read_b128 v[202:205], v243 offset:8832
	ds_read_b128 v[214:217], v207 offset:4096
	v_add_u32_e32 v218, s15, v238
	v_add_u32_e32 v219, s15, v239
	s_waitcnt lgkmcnt(5)
	v_mfma_f32_32x32x16_bf16 v[146:161], v[244:247], v[162:165], 0
	s_waitcnt lgkmcnt(4)
	v_mfma_f32_32x32x16_bf16 v[146:161], v[248:251], v[166:169], v[146:161]
	ds_read_b128 v[244:247], v243 offset:8864
	ds_read_b128 v[248:251], v207 offset:5120
	s_waitcnt lgkmcnt(5)
	v_mfma_f32_32x32x16_bf16 v[146:161], v[194:197], v[170:173], v[146:161]
	s_waitcnt lgkmcnt(4)
	v_mfma_f32_32x32x16_bf16 v[146:161], v[198:201], v[174:177], v[146:161]
	ds_read_b128 v[194:197], v243 offset:8896
	ds_read_b128 v[198:201], v207 offset:6144
	s_waitcnt lgkmcnt(4)
	v_mfma_f32_32x32x16_bf16 v[130:145], v[202:205], v[214:217], 0
	ds_read_b128 v[202:205], v243 offset:8928
	ds_read_b128 v[214:217], v207 offset:7168
	s_waitcnt lgkmcnt(4)
	v_mfma_f32_32x32x16_bf16 v[130:145], v[244:247], v[248:251], v[130:145]
	ds_read_b64_tr_b16 v[244:245], v218 offset:17408
	ds_read_b64_tr_b16 v[246:247], v218 offset:19968
	ds_read_b64_tr_b16 v[248:249], v218 offset:17472
	ds_read_b64_tr_b16 v[250:251], v218 offset:20032
	v_exp_f32_e32 v146, v146
	v_exp_f32_e32 v147, v147
	v_exp_f32_e32 v148, v148
	v_add_f32_e32 v220, v146, v147
	v_exp_f32_e32 v149, v149
	v_add_f32_e32 v220, v148, v220
	v_exp_f32_e32 v150, v150
	s_waitcnt lgkmcnt(6)
	v_mfma_f32_32x32x16_bf16 v[130:145], v[194:197], v[198:201], v[130:145]
	ds_read_b64_tr_b16 v[194:195], v218 offset:17536
	ds_read_b64_tr_b16 v[196:197], v218 offset:20096
	ds_read_b64_tr_b16 v[198:199], v218 offset:17600
	ds_read_b64_tr_b16 v[200:201], v218 offset:20160
	v_add_f32_e32 v220, v149, v220
	v_exp_f32_e32 v151, v151
	v_add_f32_e32 v220, v150, v220
	v_exp_f32_e32 v152, v152
	v_add_f32_e32 v220, v151, v220
	v_exp_f32_e32 v153, v153
	s_waitcnt lgkmcnt(8)
	v_mfma_f32_32x32x16_bf16 v[130:145], v[202:205], v[214:217], v[130:145]
	ds_read_b64_tr_b16 v[202:203], v219 offset:17408
	ds_read_b64_tr_b16 v[204:205], v219 offset:19968
	ds_read_b64_tr_b16 v[214:215], v219 offset:17472
	ds_read_b64_tr_b16 v[216:217], v219 offset:20032
	v_add_f32_e32 v220, v152, v220
	v_cvt_pk_bf16_f32 v146, v146, v147
	v_add_f32_e32 v220, v153, v220
	v_cvt_pk_bf16_f32 v147, v148, v149
	v_cvt_pk_bf16_f32 v148, v150, v151
	v_cvt_pk_bf16_f32 v149, v152, v153
	s_nop 1
	s_waitcnt lgkmcnt(10)
	v_mfma_f32_32x32x16_bf16 v[114:129], v[244:247], v[146:149], v[114:129]
	v_exp_f32_e32 v154, v154
	v_exp_f32_e32 v155, v155
	v_add_f32_e32 v220, v154, v220
	v_exp_f32_e32 v156, v156
	v_add_f32_e32 v220, v155, v220
	v_exp_f32_e32 v157, v157
	s_waitcnt lgkmcnt(8)
	v_mfma_f32_32x32x16_bf16 v[82:97], v[248:251], v[146:149], v[82:97]
	v_add_f32_e32 v220, v156, v220
	v_exp_f32_e32 v158, v158
	v_add_f32_e32 v220, v157, v220
	v_exp_f32_e32 v159, v159
	v_add_f32_e32 v220, v158, v220
	s_waitcnt lgkmcnt(6)
	v_mfma_f32_32x32x16_bf16 v[50:65], v[194:197], v[146:149], v[50:65]
	v_exp_f32_e32 v160, v160
	v_add_f32_e32 v220, v159, v220
	v_exp_f32_e32 v161, v161
	v_add_f32_e32 v220, v160, v220
	v_cvt_pk_bf16_f32 v150, v154, v155
	s_waitcnt lgkmcnt(4)
	v_mfma_f32_32x32x16_bf16 v[34:49], v[198:201], v[146:149], v[34:49]
	v_add_f32_e32 v220, v161, v220
	v_cvt_pk_bf16_f32 v151, v156, v157
	v_cvt_pk_bf16_f32 v152, v158, v159
	v_cvt_pk_bf16_f32 v153, v160, v161
	v_add_f32_e32 v209, v209, v220
	ds_read_b64_tr_b16 v[154:155], v219 offset:17536
	ds_read_b64_tr_b16 v[156:157], v219 offset:20096
	ds_read_b64_tr_b16 v[158:159], v219 offset:17600
	ds_read_b64_tr_b16 v[160:161], v219 offset:20160
	s_waitcnt lgkmcnt(6)
	v_mfma_f32_32x32x16_bf16 v[114:129], v[202:205], v[150:153], v[114:129]
	v_exp_f32_e32 v130, v130
	v_exp_f32_e32 v131, v131
	v_exp_f32_e32 v132, v132
	v_add_f32_e32 v213, v130, v131
	v_exp_f32_e32 v133, v133
	s_waitcnt lgkmcnt(4)
	v_mfma_f32_32x32x16_bf16 v[82:97], v[214:217], v[150:153], v[82:97]
	v_add_f32_e32 v213, v132, v213
	v_exp_f32_e32 v134, v134
	v_add_f32_e32 v213, v133, v213
	v_exp_f32_e32 v135, v135
	v_add_f32_e32 v213, v134, v213
	s_waitcnt lgkmcnt(2)
	v_mfma_f32_32x32x16_bf16 v[50:65], v[154:157], v[150:153], v[50:65]
	v_exp_f32_e32 v136, v136
	v_add_f32_e32 v213, v135, v213
	v_exp_f32_e32 v137, v137
	v_add_f32_e32 v213, v136, v213
	v_cvt_pk_bf16_f32 v130, v130, v131
	s_waitcnt lgkmcnt(0)
	v_mfma_f32_32x32x16_bf16 v[34:49], v[158:161], v[150:153], v[34:49]
	v_add_f32_e32 v213, v137, v213
	v_cvt_pk_bf16_f32 v131, v132, v133
	v_cvt_pk_bf16_f32 v132, v134, v135
	v_cvt_pk_bf16_f32 v133, v136, v137
	s_nop 1
	v_mfma_f32_32x32x16_bf16 v[98:113], v[244:247], v[130:133], v[98:113]
	v_exp_f32_e32 v138, v138
	v_exp_f32_e32 v139, v139
	v_add_f32_e32 v213, v138, v213
	v_exp_f32_e32 v140, v140
	v_add_f32_e32 v213, v139, v213
	v_exp_f32_e32 v141, v141
	ds_read_b128 v[244:247], v243 offset:0
	v_mfma_f32_32x32x16_bf16 v[66:81], v[248:251], v[130:133], v[66:81]
	v_add_f32_e32 v213, v140, v213
	v_exp_f32_e32 v142, v142
	v_add_f32_e32 v213, v141, v213
	v_exp_f32_e32 v143, v143
	v_add_f32_e32 v213, v142, v213
	ds_read_b128 v[248:251], v243 offset:32
	v_mfma_f32_32x32x16_bf16 v[18:33], v[194:197], v[130:133], v[18:33]
	v_exp_f32_e32 v144, v144
	v_add_f32_e32 v213, v143, v213
	v_exp_f32_e32 v145, v145
	v_add_f32_e32 v213, v144, v213
	v_cvt_pk_bf16_f32 v134, v138, v139
	ds_read_b128 v[194:197], v243 offset:64
	v_mfma_f32_32x32x16_bf16 v[2:17], v[198:201], v[130:133], v[2:17]
	v_add_f32_e32 v213, v145, v213
	v_cvt_pk_bf16_f32 v135, v140, v141
	v_cvt_pk_bf16_f32 v136, v142, v143
	v_cvt_pk_bf16_f32 v137, v144, v145
	v_add_f32_e32 v208, v208, v213
	ds_read_b128 v[198:201], v243 offset:96
	s_nop 1
	v_mfma_f32_32x32x16_bf16 v[98:113], v[202:205], v[134:137], v[98:113]
	s_waitcnt vmcnt(3)
; #define LAS __attribute__((address_space(3)))
; template <int MODE>
; __device__ __forceinline__ void attn_item(const AttnP& p, int b, int h, int qb, LAS unsigned char* lds) {
;     ...
;                     if (MODE == 0) {
;                         const LAS float* tab = (const LAS float*)(lds + TAB_OFF);
;                         if (qw - (kp0 + 31) >= 128) {
;                             const float cb = tab[255] - mfix;
; #pragma unroll
;                             for (int c = 0; c < NC; ++c) { ATT_QK(c, cb); ATT_TAIL(c); }
;                         } else {
;                             float binit[16];
; #pragma unroll
;                             for (int i = 0; i < 16; ++i) {
;                                 const int dist = qrow - (kp0 + crow(i, hh));
;                                 binit[i] = (dist < 0) ? -3e38f : (tab[dist > 255 ? 255 : dist] - mfix);
;                             }
; #pragma unroll
;                             for (int c = 0; c < NC; ++c) { ATT_QK(c, binit[i]); ATT_TAIL(c); }
;                         }
;                     } else {
;                         float binit[16];
;                         const LAS float* bl = (const LAS float*)(vtb + VT_BYTES) + 32 * kb2 + 4 * hh;
; #pragma unroll
;                         for (int g = 0; g < 4; ++g) {
;                             const f32x4 t = *(const LAS f32x4*)(bl + 8 * g);
; #pragma unroll
;                             for (int e = 0; e < 4; ++e) binit[4 * g + e] = (need_mask && (kp0 + crow(4 * g + e, hh) > qrow)) ? -3e38f : (t[e] - mfix);
;                         }
;                         ATT_QK(0, binit[i]); ATT_TAIL(0);
;                     }
;     ...
;                 }
; #pragma unroll
;                 for (int t2 = 0; t2 < 2; ++t2)
; #pragma unroll
;                     for (int d = 0; d < DV / 32; ++d) {
;                         const LAS unsigned char* vp = vtb + ((32 * kb2 + 16 * t2 + 4 * hh + ((lane & 15) >> 2)) * VPT + d * 32 + 16 * ((lane >> 4) & 1) + 4 * (lane & 3)) * 2;
;                         const s16x4 lo = vtr(vp), hi = vtr(vp + 8 * VPT * 2);
;                         const bf16x8 va = __builtin_shufflevector(lo, hi, 0, 1, 2, 3, 4, 5, 6, 7);
; #pragma unroll
;                         for (int c = 0; c < NC; ++c) O[c][d] = MFMA32(va, pb[c][t2], O[c][d]);
;                     }
	v_and_b32_e32 v138, 0xffff0000, v181
	v_lshlrev_b32_e32 v142, 16, v181
	v_mul_f32_e32 v138, v138, v138
	v_fmac_f32_e32 v138, v142, v142
	v_and_b32_e32 v139, 0xffff0000, v180
	ds_read_b128 v[202:205], v243 offset:128
	v_mfma_f32_32x32x16_bf16 v[66:81], v[214:217], v[134:137], v[66:81]
	v_lshlrev_b32_e32 v142, 16, v180
	v_mul_f32_e32 v139, v139, v139
	v_fmac_f32_e32 v139, v142, v142
	v_and_b32_e32 v140, 0xffff0000, v178
	v_lshlrev_b32_e32 v142, 16, v178
	v_mul_f32_e32 v140, v140, v140
	ds_read_b128 v[214:217], v207 offset:4096
	v_mfma_f32_32x32x16_bf16 v[18:33], v[154:157], v[134:137], v[18:33]
	v_fmac_f32_e32 v140, v142, v142
	v_and_b32_e32 v141, 0xffff0000, v179
	v_lshlrev_b32_e32 v142, 16, v179
	v_mul_f32_e32 v141, v141, v141
	v_fmac_f32_e32 v141, v142, v142
	v_add_f32_e32 v140, v140, v141
	v_mfma_f32_32x32x16_bf16 v[2:17], v[158:161], v[134:137], v[2:17]
	v_add_f32_e32 v139, v139, v140
	v_add_f32_e32 v138, v138, v139
	s_nop 1
	v_add_f32_dpp v138, v138, v138 quad_perm:[1,0,3,2] row_mask:0xf bank_mask:0xf bound_ctrl:1
	s_nop 1
	v_add_f32_dpp v138, v138, v138 quad_perm:[2,3,0,1] row_mask:0xf bank_mask:0xf bound_ctrl:1
	v_add_u32_e32 v218, s15, v237
	v_add_u32_e32 v219, s15, v240
	s_waitcnt lgkmcnt(5)
	v_mfma_f32_32x32x16_bf16 v[146:161], v[244:247], v[162:165], 0
	s_nop 1
	v_add_f32_dpp v138, v138, v138 row_half_mirror row_mask:0xf bank_mask:0xf bound_ctrl:1
	v_fmamk_f32 v138, v138, 0x3c800000, v211
	v_rsq_f32_e32 v138, v138
	v_lshlrev_b32_e32 v139, 16, v178
	v_and_b32_e32 v140, 0xffff0000, v178
	s_waitcnt lgkmcnt(4)
	v_mfma_f32_32x32x16_bf16 v[146:161], v[248:251], v[166:169], v[146:161]
	v_mul_f32_e32 v139, v138, v139
	v_mul_f32_e32 v140, v138, v140
	v_cvt_pk_bf16_f32 v178, v139, v140
	v_lshlrev_b32_e32 v139, 16, v179
	v_and_b32_e32 v140, 0xffff0000, v179
	v_mul_f32_e32 v139, v138, v139
	ds_read_b128 v[244:247], v243 offset:160
	ds_read_b128 v[248:251], v207 offset:5120
	s_waitcnt lgkmcnt(5)
	v_mfma_f32_32x32x16_bf16 v[146:161], v[194:197], v[170:173], v[146:161]
	v_mul_f32_e32 v140, v138, v140
	v_cvt_pk_bf16_f32 v179, v139, v140
	v_lshlrev_b32_e32 v139, 16, v180
	v_and_b32_e32 v140, 0xffff0000, v180
	v_mul_f32_e32 v139, v138, v139
	v_mul_f32_e32 v140, v138, v140
	s_waitcnt lgkmcnt(4)
	v_mfma_f32_32x32x16_bf16 v[146:161], v[198:201], v[174:177], v[146:161]
	v_cvt_pk_bf16_f32 v180, v139, v140
	v_lshlrev_b32_e32 v139, 16, v181
	v_and_b32_e32 v140, 0xffff0000, v181
	v_mul_f32_e32 v139, v138, v139
	v_mul_f32_e32 v140, v138, v140
	v_cvt_pk_bf16_f32 v181, v139, v140
	v_add_u32_e32 v139, s2, v231
	ds_write_b128 v139, v[178:181]
	ds_read_b128 v[194:197], v243 offset:192
	ds_read_b128 v[198:201], v207 offset:6144
	s_waitcnt lgkmcnt(5)
	v_mfma_f32_32x32x16_bf16 v[130:145], v[202:205], v[214:217], 0
	ds_read_b128 v[202:205], v243 offset:224
	ds_read_b128 v[214:217], v207 offset:7168
	s_waitcnt lgkmcnt(5)
	v_mfma_f32_32x32x16_bf16 v[130:145], v[244:247], v[248:251], v[130:145]
	ds_read_b64_tr_b16 v[244:245], v218 offset:17408
	ds_read_b64_tr_b16 v[246:247], v218 offset:19968
	ds_read_b64_tr_b16 v[248:249], v218 offset:17472
	ds_read_b64_tr_b16 v[250:251], v218 offset:20032
	v_exp_f32_e32 v146, v146
	v_exp_f32_e32 v147, v147
	v_exp_f32_e32 v148, v148
	v_add_f32_e32 v220, v146, v147
	v_exp_f32_e32 v149, v149
	v_add_f32_e32 v220, v148, v220
	v_exp_f32_e32 v150, v150
	s_waitcnt lgkmcnt(6)
	v_mfma_f32_32x32x16_bf16 v[130:145], v[194:197], v[198:201], v[130:145]
	ds_read_b64_tr_b16 v[194:195], v218 offset:17536
	ds_read_b64_tr_b16 v[196:197], v218 offset:20096
	ds_read_b64_tr_b16 v[198:199], v218 offset:17600
	ds_read_b64_tr_b16 v[200:201], v218 offset:20160
	v_add_f32_e32 v220, v149, v220
	v_exp_f32_e32 v151, v151
	v_add_f32_e32 v220, v150, v220
	v_exp_f32_e32 v152, v152
	v_add_f32_e32 v220, v151, v220
	v_exp_f32_e32 v153, v153
	s_waitcnt lgkmcnt(8)
	v_mfma_f32_32x32x16_bf16 v[130:145], v[202:205], v[214:217], v[130:145]
	ds_read_b64_tr_b16 v[202:203], v219 offset:17408
	ds_read_b64_tr_b16 v[204:205], v219 offset:19968
	ds_read_b64_tr_b16 v[214:215], v219 offset:17472
	ds_read_b64_tr_b16 v[216:217], v219 offset:20032
	v_add_f32_e32 v220, v152, v220
	v_cvt_pk_bf16_f32 v146, v146, v147
	v_add_f32_e32 v220, v153, v220
	v_cvt_pk_bf16_f32 v147, v148, v149
	v_cvt_pk_bf16_f32 v148, v150, v151
	v_cvt_pk_bf16_f32 v149, v152, v153
	s_nop 1
	s_waitcnt lgkmcnt(10)
	v_mfma_f32_32x32x16_bf16 v[114:129], v[244:247], v[146:149], v[114:129]
	v_exp_f32_e32 v154, v154
	v_exp_f32_e32 v155, v155
	v_add_f32_e32 v220, v154, v220
	v_exp_f32_e32 v156, v156
	v_add_f32_e32 v220, v155, v220
	v_exp_f32_e32 v157, v157
	s_waitcnt lgkmcnt(8)
	v_mfma_f32_32x32x16_bf16 v[82:97], v[248:251], v[146:149], v[82:97]
	v_add_f32_e32 v220, v156, v220
	v_exp_f32_e32 v158, v158
	v_add_f32_e32 v220, v157, v220
	v_exp_f32_e32 v159, v159
	v_add_f32_e32 v220, v158, v220
	s_waitcnt lgkmcnt(6)
	v_mfma_f32_32x32x16_bf16 v[50:65], v[194:197], v[146:149], v[50:65]
	v_exp_f32_e32 v160, v160
	v_add_f32_e32 v220, v159, v220
	v_exp_f32_e32 v161, v161
	v_add_f32_e32 v220, v160, v220
	v_cvt_pk_bf16_f32 v150, v154, v155
	s_waitcnt lgkmcnt(4)
	v_mfma_f32_32x32x16_bf16 v[34:49], v[198:201], v[146:149], v[34:49]
	v_add_f32_e32 v220, v161, v220
	v_cvt_pk_bf16_f32 v151, v156, v157
	v_cvt_pk_bf16_f32 v152, v158, v159
	v_cvt_pk_bf16_f32 v153, v160, v161
	v_add_f32_e32 v209, v209, v220
	ds_read_b64_tr_b16 v[154:155], v219 offset:17536
	ds_read_b64_tr_b16 v[156:157], v219 offset:20096
	ds_read_b64_tr_b16 v[158:159], v219 offset:17600
	ds_read_b64_tr_b16 v[160:161], v219 offset:20160
	s_waitcnt lgkmcnt(6)
; #define LAS __attribute__((address_space(3)))
; #define MFMA32(a, b, c) __builtin_amdgcn_mfma_f32_32x32x16_bf16((a), (b), (c), 0, 0, 0)
; __device__ __forceinline__ s16x4 vtr(const LAS unsigned char* p) { return __builtin_bit_cast(s16x4, __builtin_amdgcn_ds_read_tr16_b64_v4i16((LAS v4i16_t*)p)); }
; template <int MODE>
; __device__ __forceinline__ void attn_item(const AttnP& p, int b, int h, int qb, LAS unsigned char* lds) {
;     ...
; #pragma unroll
;                 for (int t2 = 0; t2 < 2; ++t2)
; #pragma unroll
;                     for (int d = 0; d < DV / 32; ++d) {
;                         const LAS unsigned char* vp = vtb + ((32 * kb2 + 16 * t2 + 4 * hh + ((lane & 15) >> 2)) * VPT + d * 32 + 16 * ((lane >> 4) & 1) + 4 * (lane & 3)) * 2;
;                         const s16x4 lo = vtr(vp), hi = vtr(vp + 8 * VPT * 2);
;                         const bf16x8 va = __builtin_shufflevector(lo, hi, 0, 1, 2, 3, 4, 5, 6, 7);
; #pragma unroll
;                         for (int c = 0; c < NC; ++c) O[c][d] = MFMA32(va, pb[c][t2], O[c][d]);
;                     }
	v_mfma_f32_32x32x16_bf16 v[114:129], v[202:205], v[150:153], v[114:129]
	v_exp_f32_e32 v130, v130
	v_exp_f32_e32 v131, v131
	v_exp_f32_e32 v132, v132
	v_add_f32_e32 v213, v130, v131
	v_exp_f32_e32 v133, v133
	s_waitcnt lgkmcnt(4)
	v_mfma_f32_32x32x16_bf16 v[82:97], v[214:217], v[150:153], v[82:97]
	v_add_f32_e32 v213, v132, v213
	v_exp_f32_e32 v134, v134
	v_add_f32_e32 v213, v133, v213
	v_exp_f32_e32 v135, v135
	v_add_f32_e32 v213, v134, v213
	s_waitcnt lgkmcnt(2)
	v_mfma_f32_32x32x16_bf16 v[50:65], v[154:157], v[150:153], v[50:65]
	v_exp_f32_e32 v136, v136
	v_add_f32_e32 v213, v135, v213
	v_exp_f32_e32 v137, v137
	v_add_f32_e32 v213, v136, v213
	v_cvt_pk_bf16_f32 v130, v130, v131
	s_waitcnt lgkmcnt(0)
	v_mfma_f32_32x32x16_bf16 v[34:49], v[158:161], v[150:153], v[34:49]
	v_add_f32_e32 v213, v137, v213
	v_cvt_pk_bf16_f32 v131, v132, v133
	v_cvt_pk_bf16_f32 v132, v134, v135
	v_cvt_pk_bf16_f32 v133, v136, v137
	s_nop 1
	v_mfma_f32_32x32x16_bf16 v[98:113], v[244:247], v[130:133], v[98:113]
	v_exp_f32_e32 v138, v138
	v_exp_f32_e32 v139, v139
	v_add_f32_e32 v213, v138, v213
	v_exp_f32_e32 v140, v140
	v_add_f32_e32 v213, v139, v213
	v_exp_f32_e32 v141, v141
	v_mfma_f32_32x32x16_bf16 v[66:81], v[248:251], v[130:133], v[66:81]
	v_add_f32_e32 v213, v140, v213
	v_exp_f32_e32 v142, v142
	v_add_f32_e32 v213, v141, v213
	v_exp_f32_e32 v143, v143
	v_add_f32_e32 v213, v142, v213
	v_mfma_f32_32x32x16_bf16 v[18:33], v[194:197], v[130:133], v[18:33]
	v_exp_f32_e32 v144, v144
	v_add_f32_e32 v213, v143, v213
	v_exp_f32_e32 v145, v145
	v_add_f32_e32 v213, v144, v213
	v_cvt_pk_bf16_f32 v134, v138, v139
	v_mfma_f32_32x32x16_bf16 v[2:17], v[198:201], v[130:133], v[2:17]
	v_add_f32_e32 v213, v145, v213
	v_cvt_pk_bf16_f32 v135, v140, v141
	v_cvt_pk_bf16_f32 v136, v142, v143
	v_cvt_pk_bf16_f32 v137, v144, v145
	v_add_f32_e32 v208, v208, v213
	s_nop 1
	v_mfma_f32_32x32x16_bf16 v[98:113], v[202:205], v[134:137], v[98:113]
	s_waitcnt vmcnt(2)
	v_and_b32_e32 v138, 0xffff0000, v185
	v_lshlrev_b32_e32 v142, 16, v185
	v_mul_f32_e32 v138, v138, v138
	v_fmac_f32_e32 v138, v142, v142
	v_and_b32_e32 v139, 0xffff0000, v184
	v_mfma_f32_32x32x16_bf16 v[66:81], v[214:217], v[134:137], v[66:81]
	v_lshlrev_b32_e32 v142, 16, v184
	v_mul_f32_e32 v139, v139, v139
	v_fmac_f32_e32 v139, v142, v142
	v_and_b32_e32 v140, 0xffff0000, v182
	v_lshlrev_b32_e32 v142, 16, v182
	v_mul_f32_e32 v140, v140, v140
	v_mfma_f32_32x32x16_bf16 v[18:33], v[154:157], v[134:137], v[18:33]
	v_fmac_f32_e32 v140, v142, v142
	v_and_b32_e32 v141, 0xffff0000, v183
	v_lshlrev_b32_e32 v142, 16, v183
	v_mul_f32_e32 v141, v141, v141
	v_fmac_f32_e32 v141, v142, v142
	v_add_f32_e32 v140, v140, v141
	v_mfma_f32_32x32x16_bf16 v[2:17], v[158:161], v[134:137], v[2:17]
	v_add_f32_e32 v139, v139, v140
	v_add_f32_e32 v138, v138, v139
	s_nop 1
	v_add_f32_dpp v138, v138, v138 quad_perm:[1,0,3,2] row_mask:0xf bank_mask:0xf bound_ctrl:1
	s_nop 1
	v_add_f32_dpp v138, v138, v138 quad_perm:[2,3,0,1] row_mask:0xf bank_mask:0xf bound_ctrl:1
	s_nop 1
	v_add_f32_dpp v138, v138, v138 row_half_mirror row_mask:0xf bank_mask:0xf bound_ctrl:1
	v_fmamk_f32 v138, v138, 0x3c800000, v211
	v_rsq_f32_e32 v138, v138
	v_lshlrev_b32_e32 v139, 16, v182
	v_and_b32_e32 v140, 0xffff0000, v182
	v_mul_f32_e32 v139, v138, v139
	v_mul_f32_e32 v140, v138, v140
	v_cvt_pk_bf16_f32 v182, v139, v140
	v_lshlrev_b32_e32 v139, 16, v183
	v_and_b32_e32 v140, 0xffff0000, v183
	v_mul_f32_e32 v139, v138, v139
	v_mul_f32_e32 v140, v138, v140
	v_cvt_pk_bf16_f32 v183, v139, v140
	v_lshlrev_b32_e32 v139, 16, v184
	v_and_b32_e32 v140, 0xffff0000, v184
	v_mul_f32_e32 v139, v138, v139
	v_mul_f32_e32 v140, v138, v140
	v_cvt_pk_bf16_f32 v184, v139, v140
	v_lshlrev_b32_e32 v139, 16, v185
	v_and_b32_e32 v140, 0xffff0000, v185
	v_mul_f32_e32 v139, v138, v139
	v_mul_f32_e32 v140, v138, v140
	v_cvt_pk_bf16_f32 v185, v139, v140
	v_add_u32_e32 v139, s2, v233
	ds_write_b128 v139, v[182:185]
	s_waitcnt vmcnt(1)
	v_add_u32_e32 v143, s2, v232
	ds_write_b128 v143, v[186:189] offset:17408
	s_waitcnt vmcnt(0)
	v_add_u32_e32 v144, s2, v234
	ds_write_b128 v144, v[190:193] offset:17408
	s_branch .LBB0_495
.Lfar_tile_last:
	v_add_u32_e32 v243, v242, v235
	ds_read_b128 v[244:247], v243 offset:8704
	ds_read_b128 v[248:251], v243 offset:8736
	ds_read_b128 v[194:197], v243 offset:8768
	ds_read_b128 v[198:201], v243 offset:8800
	ds_read_b128 v[202:205], v243 offset:8832
	ds_read_b128 v[214:217], v207 offset:4096
	v_add_u32_e32 v218, s15, v238
	v_add_u32_e32 v219, s15, v239
	s_waitcnt lgkmcnt(5)
	v_mfma_f32_32x32x16_bf16 v[146:161], v[244:247], v[162:165], 0
	s_waitcnt lgkmcnt(4)
	v_mfma_f32_32x32x16_bf16 v[146:161], v[248:251], v[166:169], v[146:161]
	ds_read_b128 v[244:247], v243 offset:8864
	ds_read_b128 v[248:251], v207 offset:5120
	s_waitcnt lgkmcnt(5)
	v_mfma_f32_32x32x16_bf16 v[146:161], v[194:197], v[170:173], v[146:161]
	s_waitcnt lgkmcnt(4)
	v_mfma_f32_32x32x16_bf16 v[146:161], v[198:201], v[174:177], v[146:161]
	ds_read_b128 v[194:197], v243 offset:8896
	ds_read_b128 v[198:201], v207 offset:6144
	s_waitcnt lgkmcnt(4)
	v_mfma_f32_32x32x16_bf16 v[130:145], v[202:205], v[214:217], 0
	ds_read_b128 v[202:205], v243 offset:8928
	ds_read_b128 v[214:217], v207 offset:7168
	s_waitcnt lgkmcnt(4)
	v_mfma_f32_32x32x16_bf16 v[130:145], v[244:247], v[248:251], v[130:145]
	ds_read_b64_tr_b16 v[244:245], v218 offset:17408
	ds_read_b64_tr_b16 v[246:247], v218 offset:19968
	ds_read_b64_tr_b16 v[248:249], v218 offset:17472
	ds_read_b64_tr_b16 v[250:251], v218 offset:20032
	v_exp_f32_e32 v146, v146
	v_exp_f32_e32 v147, v147
	v_exp_f32_e32 v148, v148
	v_add_f32_e32 v220, v146, v147
	v_exp_f32_e32 v149, v149
	v_add_f32_e32 v220, v148, v220
	v_exp_f32_e32 v150, v150
	s_waitcnt lgkmcnt(6)
; #define LAS __attribute__((address_space(3)))
; template <int MODE>
; __device__ __forceinline__ void attn_item(const AttnP& p, int b, int h, int qb, LAS unsigned char* lds) {
;     ...
;                     if (MODE == 0) {
;                         const LAS float* tab = (const LAS float*)(lds + TAB_OFF);
;                         if (qw - (kp0 + 31) >= 128) {
;                             const float cb = tab[255] - mfix;
; #pragma unroll
;                             for (int c = 0; c < NC; ++c) { ATT_QK(c, cb); ATT_TAIL(c); }
;                         } else {
;                             float binit[16];
; #pragma unroll
;                             for (int i = 0; i < 16; ++i) {
;                                 const int dist = qrow - (kp0 + crow(i, hh));
;                                 binit[i] = (dist < 0) ? -3e38f : (tab[dist > 255 ? 255 : dist] - mfix);
;                             }
; #pragma unroll
;                             for (int c = 0; c < NC; ++c) { ATT_QK(c, binit[i]); ATT_TAIL(c); }
;                         }
;                     } else {
;                         float binit[16];
;                         const LAS float* bl = (const LAS float*)(vtb + VT_BYTES) + 32 * kb2 + 4 * hh;
; #pragma unroll
;                         for (int g = 0; g < 4; ++g) {
;                             const f32x4 t = *(const LAS f32x4*)(bl + 8 * g);
; #pragma unroll
;                             for (int e = 0; e < 4; ++e) binit[4 * g + e] = (need_mask && (kp0 + crow(4 * g + e, hh) > qrow)) ? -3e38f : (t[e] - mfix);
;                         }
;                         ATT_QK(0, binit[i]); ATT_TAIL(0);
;                     }
;     ...
;                 }
; #pragma unroll
;                 for (int t2 = 0; t2 < 2; ++t2)
; #pragma unroll
;                     for (int d = 0; d < DV / 32; ++d) {
;                         const LAS unsigned char* vp = vtb + ((32 * kb2 + 16 * t2 + 4 * hh + ((lane & 15) >> 2)) * VPT + d * 32 + 16 * ((lane >> 4) & 1) + 4 * (lane & 3)) * 2;
;                         const s16x4 lo = vtr(vp), hi = vtr(vp + 8 * VPT * 2);
;                         const bf16x8 va = __builtin_shufflevector(lo, hi, 0, 1, 2, 3, 4, 5, 6, 7);
; #pragma unroll
;                         for (int c = 0; c < NC; ++c) O[c][d] = MFMA32(va, pb[c][t2], O[c][d]);
;                     }
	v_mfma_f32_32x32x16_bf16 v[130:145], v[194:197], v[198:201], v[130:145]
	ds_read_b64_tr_b16 v[194:195], v218 offset:17536
	ds_read_b64_tr_b16 v[196:197], v218 offset:20096
	ds_read_b64_tr_b16 v[198:199], v218 offset:17600
	ds_read_b64_tr_b16 v[200:201], v218 offset:20160
	v_add_f32_e32 v220, v149, v220
	v_exp_f32_e32 v151, v151
	v_add_f32_e32 v220, v150, v220
	v_exp_f32_e32 v152, v152
	v_add_f32_e32 v220, v151, v220
	v_exp_f32_e32 v153, v153
	s_waitcnt lgkmcnt(8)
	v_mfma_f32_32x32x16_bf16 v[130:145], v[202:205], v[214:217], v[130:145]
	ds_read_b64_tr_b16 v[202:203], v219 offset:17408
	ds_read_b64_tr_b16 v[204:205], v219 offset:19968
	ds_read_b64_tr_b16 v[214:215], v219 offset:17472
	ds_read_b64_tr_b16 v[216:217], v219 offset:20032
	v_add_f32_e32 v220, v152, v220
	v_cvt_pk_bf16_f32 v146, v146, v147
	v_add_f32_e32 v220, v153, v220
	v_cvt_pk_bf16_f32 v147, v148, v149
	v_cvt_pk_bf16_f32 v148, v150, v151
	v_cvt_pk_bf16_f32 v149, v152, v153
	s_nop 1
	s_waitcnt lgkmcnt(10)
	v_mfma_f32_32x32x16_bf16 v[114:129], v[244:247], v[146:149], v[114:129]
	v_exp_f32_e32 v154, v154
	v_exp_f32_e32 v155, v155
	v_add_f32_e32 v220, v154, v220
	v_exp_f32_e32 v156, v156
	v_add_f32_e32 v220, v155, v220
	v_exp_f32_e32 v157, v157
	s_waitcnt lgkmcnt(8)
	v_mfma_f32_32x32x16_bf16 v[82:97], v[248:251], v[146:149], v[82:97]
	v_add_f32_e32 v220, v156, v220
	v_exp_f32_e32 v158, v158
	v_add_f32_e32 v220, v157, v220
	v_exp_f32_e32 v159, v159
	v_add_f32_e32 v220, v158, v220
	s_waitcnt lgkmcnt(6)
	v_mfma_f32_32x32x16_bf16 v[50:65], v[194:197], v[146:149], v[50:65]
	v_exp_f32_e32 v160, v160
	v_add_f32_e32 v220, v159, v220
	v_exp_f32_e32 v161, v161
	v_add_f32_e32 v220, v160, v220
	v_cvt_pk_bf16_f32 v150, v154, v155
	s_waitcnt lgkmcnt(4)
	v_mfma_f32_32x32x16_bf16 v[34:49], v[198:201], v[146:149], v[34:49]
	v_add_f32_e32 v220, v161, v220
	v_cvt_pk_bf16_f32 v151, v156, v157
	v_cvt_pk_bf16_f32 v152, v158, v159
	v_cvt_pk_bf16_f32 v153, v160, v161
	v_add_f32_e32 v209, v209, v220
	ds_read_b64_tr_b16 v[154:155], v219 offset:17536
	ds_read_b64_tr_b16 v[156:157], v219 offset:20096
	ds_read_b64_tr_b16 v[158:159], v219 offset:17600
	ds_read_b64_tr_b16 v[160:161], v219 offset:20160
	s_waitcnt lgkmcnt(6)
	v_mfma_f32_32x32x16_bf16 v[114:129], v[202:205], v[150:153], v[114:129]
	v_exp_f32_e32 v130, v130
	v_exp_f32_e32 v131, v131
	v_exp_f32_e32 v132, v132
	v_add_f32_e32 v213, v130, v131
	v_exp_f32_e32 v133, v133
	s_waitcnt lgkmcnt(4)
	v_mfma_f32_32x32x16_bf16 v[82:97], v[214:217], v[150:153], v[82:97]
	v_add_f32_e32 v213, v132, v213
	v_exp_f32_e32 v134, v134
	v_add_f32_e32 v213, v133, v213
	v_exp_f32_e32 v135, v135
	v_add_f32_e32 v213, v134, v213
	s_waitcnt lgkmcnt(2)
	v_mfma_f32_32x32x16_bf16 v[50:65], v[154:157], v[150:153], v[50:65]
	v_exp_f32_e32 v136, v136
	v_add_f32_e32 v213, v135, v213
	v_exp_f32_e32 v137, v137
	v_add_f32_e32 v213, v136, v213
	v_cvt_pk_bf16_f32 v130, v130, v131
	s_waitcnt lgkmcnt(0)
	v_mfma_f32_32x32x16_bf16 v[34:49], v[158:161], v[150:153], v[34:49]
	v_add_f32_e32 v213, v137, v213
	v_cvt_pk_bf16_f32 v131, v132, v133
	v_cvt_pk_bf16_f32 v132, v134, v135
	v_cvt_pk_bf16_f32 v133, v136, v137
	s_nop 1
	v_mfma_f32_32x32x16_bf16 v[98:113], v[244:247], v[130:133], v[98:113]
	v_exp_f32_e32 v138, v138
	v_exp_f32_e32 v139, v139
	v_add_f32_e32 v213, v138, v213
	v_exp_f32_e32 v140, v140
	v_add_f32_e32 v213, v139, v213
	v_exp_f32_e32 v141, v141
	ds_read_b128 v[244:247], v243 offset:0
	v_mfma_f32_32x32x16_bf16 v[66:81], v[248:251], v[130:133], v[66:81]
	v_add_f32_e32 v213, v140, v213
	v_exp_f32_e32 v142, v142
	v_add_f32_e32 v213, v141, v213
	v_exp_f32_e32 v143, v143
	v_add_f32_e32 v213, v142, v213
	ds_read_b128 v[248:251], v243 offset:32
	v_mfma_f32_32x32x16_bf16 v[18:33], v[194:197], v[130:133], v[18:33]
	v_exp_f32_e32 v144, v144
	v_add_f32_e32 v213, v143, v213
	v_exp_f32_e32 v145, v145
	v_add_f32_e32 v213, v144, v213
	v_cvt_pk_bf16_f32 v134, v138, v139
	ds_read_b128 v[194:197], v243 offset:64
	v_mfma_f32_32x32x16_bf16 v[2:17], v[198:201], v[130:133], v[2:17]
	v_add_f32_e32 v213, v145, v213
	v_cvt_pk_bf16_f32 v135, v140, v141
	v_cvt_pk_bf16_f32 v136, v142, v143
	v_cvt_pk_bf16_f32 v137, v144, v145
	v_add_f32_e32 v208, v208, v213
	ds_read_b128 v[198:201], v243 offset:96
	s_nop 1
	v_mfma_f32_32x32x16_bf16 v[98:113], v[202:205], v[134:137], v[98:113]
	ds_read_b128 v[202:205], v243 offset:128
	v_mfma_f32_32x32x16_bf16 v[66:81], v[214:217], v[134:137], v[66:81]
	ds_read_b128 v[214:217], v207 offset:4096
	v_mfma_f32_32x32x16_bf16 v[18:33], v[154:157], v[134:137], v[18:33]
	v_mfma_f32_32x32x16_bf16 v[2:17], v[158:161], v[134:137], v[2:17]
	v_add_u32_e32 v218, s15, v237
	v_add_u32_e32 v219, s15, v240
	s_waitcnt lgkmcnt(5)
	v_mfma_f32_32x32x16_bf16 v[146:161], v[244:247], v[162:165], 0
	s_waitcnt lgkmcnt(4)
	v_mfma_f32_32x32x16_bf16 v[146:161], v[248:251], v[166:169], v[146:161]
	ds_read_b128 v[244:247], v243 offset:160
	ds_read_b128 v[248:251], v207 offset:5120
	s_waitcnt lgkmcnt(5)
	v_mfma_f32_32x32x16_bf16 v[146:161], v[194:197], v[170:173], v[146:161]
	s_waitcnt lgkmcnt(4)
; #define LAS __attribute__((address_space(3)))
; #define MFMA32(a, b, c) __builtin_amdgcn_mfma_f32_32x32x16_bf16((a), (b), (c), 0, 0, 0)
; __device__ __forceinline__ s16x4 vtr(const LAS unsigned char* p) { return __builtin_bit_cast(s16x4, __builtin_amdgcn_ds_read_tr16_b64_v4i16((LAS v4i16_t*)p)); }
; template <int MODE>
; __device__ __forceinline__ void attn_item(const AttnP& p, int b, int h, int qb, LAS unsigned char* lds) {
;     ...
;                         if (qw - (kp0 + 31) >= 128) {
;                             const float cb = tab[255] - mfix;
; #pragma unroll
;                             for (int c = 0; c < NC; ++c) { ATT_QK(c, cb); ATT_TAIL(c); }
;     ...
; #pragma unroll
;                 for (int t2 = 0; t2 < 2; ++t2)
; #pragma unroll
;                     for (int d = 0; d < DV / 32; ++d) {
;                         const LAS unsigned char* vp = vtb + ((32 * kb2 + 16 * t2 + 4 * hh + ((lane & 15) >> 2)) * VPT + d * 32 + 16 * ((lane >> 4) & 1) + 4 * (lane & 3)) * 2;
;                         const s16x4 lo = vtr(vp), hi = vtr(vp + 8 * VPT * 2);
;                         const bf16x8 va = __builtin_shufflevector(lo, hi, 0, 1, 2, 3, 4, 5, 6, 7);
; #pragma unroll
;                         for (int c = 0; c < NC; ++c) O[c][d] = MFMA32(va, pb[c][t2], O[c][d]);
;                     }
	v_mfma_f32_32x32x16_bf16 v[146:161], v[198:201], v[174:177], v[146:161]
	ds_read_b128 v[194:197], v243 offset:192
	ds_read_b128 v[198:201], v207 offset:6144
	s_waitcnt lgkmcnt(4)
	v_mfma_f32_32x32x16_bf16 v[130:145], v[202:205], v[214:217], 0
	ds_read_b128 v[202:205], v243 offset:224
	ds_read_b128 v[214:217], v207 offset:7168
	s_waitcnt lgkmcnt(4)
	v_mfma_f32_32x32x16_bf16 v[130:145], v[244:247], v[248:251], v[130:145]
	ds_read_b64_tr_b16 v[244:245], v218 offset:17408
	ds_read_b64_tr_b16 v[246:247], v218 offset:19968
	ds_read_b64_tr_b16 v[248:249], v218 offset:17472
	ds_read_b64_tr_b16 v[250:251], v218 offset:20032
	v_exp_f32_e32 v146, v146
	v_exp_f32_e32 v147, v147
	v_exp_f32_e32 v148, v148
	v_add_f32_e32 v220, v146, v147
	v_exp_f32_e32 v149, v149
	v_add_f32_e32 v220, v148, v220
	v_exp_f32_e32 v150, v150
	s_waitcnt lgkmcnt(6)
	v_mfma_f32_32x32x16_bf16 v[130:145], v[194:197], v[198:201], v[130:145]
	ds_read_b64_tr_b16 v[194:195], v218 offset:17536
	ds_read_b64_tr_b16 v[196:197], v218 offset:20096
	ds_read_b64_tr_b16 v[198:199], v218 offset:17600
	ds_read_b64_tr_b16 v[200:201], v218 offset:20160
	v_add_f32_e32 v220, v149, v220
	v_exp_f32_e32 v151, v151
	v_add_f32_e32 v220, v150, v220
	v_exp_f32_e32 v152, v152
	v_add_f32_e32 v220, v151, v220
	v_exp_f32_e32 v153, v153
	s_waitcnt lgkmcnt(8)
	v_mfma_f32_32x32x16_bf16 v[130:145], v[202:205], v[214:217], v[130:145]
	ds_read_b64_tr_b16 v[202:203], v219 offset:17408
	ds_read_b64_tr_b16 v[204:205], v219 offset:19968
	ds_read_b64_tr_b16 v[214:215], v219 offset:17472
	ds_read_b64_tr_b16 v[216:217], v219 offset:20032
	v_add_f32_e32 v220, v152, v220
	v_cvt_pk_bf16_f32 v146, v146, v147
	v_add_f32_e32 v220, v153, v220
	v_cvt_pk_bf16_f32 v147, v148, v149
	v_cvt_pk_bf16_f32 v148, v150, v151
	v_cvt_pk_bf16_f32 v149, v152, v153
	s_nop 1
	s_waitcnt lgkmcnt(10)
	v_mfma_f32_32x32x16_bf16 v[114:129], v[244:247], v[146:149], v[114:129]
	v_exp_f32_e32 v154, v154
	v_exp_f32_e32 v155, v155
	v_add_f32_e32 v220, v154, v220
	v_exp_f32_e32 v156, v156
	v_add_f32_e32 v220, v155, v220
	v_exp_f32_e32 v157, v157
	s_waitcnt lgkmcnt(8)
	v_mfma_f32_32x32x16_bf16 v[82:97], v[248:251], v[146:149], v[82:97]
	v_add_f32_e32 v220, v156, v220
	v_exp_f32_e32 v158, v158
	v_add_f32_e32 v220, v157, v220
	v_exp_f32_e32 v159, v159
	v_add_f32_e32 v220, v158, v220
	s_waitcnt lgkmcnt(6)
	v_mfma_f32_32x32x16_bf16 v[50:65], v[194:197], v[146:149], v[50:65]
	v_exp_f32_e32 v160, v160
	v_add_f32_e32 v220, v159, v220
	v_exp_f32_e32 v161, v161
	v_add_f32_e32 v220, v160, v220
	v_cvt_pk_bf16_f32 v150, v154, v155
	s_waitcnt lgkmcnt(4)
	v_mfma_f32_32x32x16_bf16 v[34:49], v[198:201], v[146:149], v[34:49]
	v_add_f32_e32 v220, v161, v220
	v_cvt_pk_bf16_f32 v151, v156, v157
	v_cvt_pk_bf16_f32 v152, v158, v159
	v_cvt_pk_bf16_f32 v153, v160, v161
	v_add_f32_e32 v209, v209, v220
	ds_read_b64_tr_b16 v[154:155], v219 offset:17536
	ds_read_b64_tr_b16 v[156:157], v219 offset:20096
	ds_read_b64_tr_b16 v[158:159], v219 offset:17600
	ds_read_b64_tr_b16 v[160:161], v219 offset:20160
	s_waitcnt lgkmcnt(6)
	v_mfma_f32_32x32x16_bf16 v[114:129], v[202:205], v[150:153], v[114:129]
	v_exp_f32_e32 v130, v130
	v_exp_f32_e32 v131, v131
	v_exp_f32_e32 v132, v132
	v_add_f32_e32 v213, v130, v131
	v_exp_f32_e32 v133, v133
	s_waitcnt lgkmcnt(4)
	v_mfma_f32_32x32x16_bf16 v[82:97], v[214:217], v[150:153], v[82:97]
	v_add_f32_e32 v213, v132, v213
	v_exp_f32_e32 v134, v134
	v_add_f32_e32 v213, v133, v213
	v_exp_f32_e32 v135, v135
	v_add_f32_e32 v213, v134, v213
	s_waitcnt lgkmcnt(2)
	v_mfma_f32_32x32x16_bf16 v[50:65], v[154:157], v[150:153], v[50:65]
	v_exp_f32_e32 v136, v136
	v_add_f32_e32 v213, v135, v213
	v_exp_f32_e32 v137, v137
	v_add_f32_e32 v213, v136, v213
	v_cvt_pk_bf16_f32 v130, v130, v131
	s_waitcnt lgkmcnt(0)
	v_mfma_f32_32x32x16_bf16 v[34:49], v[158:161], v[150:153], v[34:49]
	v_add_f32_e32 v213, v137, v213
	v_cvt_pk_bf16_f32 v131, v132, v133
	v_cvt_pk_bf16_f32 v132, v134, v135
	v_cvt_pk_bf16_f32 v133, v136, v137
	s_nop 1
	v_mfma_f32_32x32x16_bf16 v[98:113], v[244:247], v[130:133], v[98:113]
	v_exp_f32_e32 v138, v138
	v_exp_f32_e32 v139, v139
	v_add_f32_e32 v213, v138, v213
	v_exp_f32_e32 v140, v140
	v_add_f32_e32 v213, v139, v213
	v_exp_f32_e32 v141, v141
	v_mfma_f32_32x32x16_bf16 v[66:81], v[248:251], v[130:133], v[66:81]
	v_add_f32_e32 v213, v140, v213
	v_exp_f32_e32 v142, v142
	v_add_f32_e32 v213, v141, v213
	v_exp_f32_e32 v143, v143
	v_add_f32_e32 v213, v142, v213
	v_mfma_f32_32x32x16_bf16 v[18:33], v[194:197], v[130:133], v[18:33]
	v_exp_f32_e32 v144, v144
	v_add_f32_e32 v213, v143, v213
	v_exp_f32_e32 v145, v145
	v_add_f32_e32 v213, v144, v213
	v_cvt_pk_bf16_f32 v134, v138, v139
	v_mfma_f32_32x32x16_bf16 v[2:17], v[198:201], v[130:133], v[2:17]
	v_add_f32_e32 v213, v145, v213
	v_cvt_pk_bf16_f32 v135, v140, v141
	v_cvt_pk_bf16_f32 v136, v142, v143
	v_cvt_pk_bf16_f32 v137, v144, v145
	v_add_f32_e32 v208, v208, v213
	s_nop 1
	v_mfma_f32_32x32x16_bf16 v[98:113], v[202:205], v[134:137], v[98:113]
	v_mfma_f32_32x32x16_bf16 v[66:81], v[214:217], v[134:137], v[66:81]
	v_mfma_f32_32x32x16_bf16 v[18:33], v[154:157], v[134:137], v[18:33]
	v_mfma_f32_32x32x16_bf16 v[2:17], v[158:161], v[134:137], v[2:17]
	s_branch .LBB0_495
